# XCD leaders no longer bump and wait for the per-XCD generation word (nobody polls it after the single-hop release)
# baseline (speedup 1.0000x reference)
; DI unsigned xb_add(unsigned* p, unsigned v) { return __hip_atomic_fetch_add(p, v, __ATOMIC_RELAXED, __HIP_MEMORY_SCOPE_AGENT); }
; DI void xcd_barrier(const XcdBarrier& b) {
;     ...
;             __builtin_amdgcn_fence(__ATOMIC_ACQUIRE, "agent");
;             xb_add(&bar[XB_XGEN(b.x)], 1u);
;             asm volatile("s_waitcnt vmcnt(0)" ::: "memory");
.LBB0_135:
	s_or_b64 exec, exec, s[8:9]
	s_mov_b64 s[8:9], exec
	v_mbcnt_lo_u32_b32 v0, s8, 0
	v_mbcnt_hi_u32_b32 v0, s9, v0
	v_cmp_eq_u32_e32 vcc, 0, v0
	s_waitcnt vmcnt(0)
	buffer_inv sc1
	s_and_saveexec_b64 s[10:11], vcc
	s_cbranch_execz .LBB0_137
	s_bcnt1_i32_b64 s8, s[8:9]
	v_mov_b32_e32 v0, 0x2000
	v_mov_b32_e32 v1, s8
.LBB0_137:
	s_or_b64 exec, exec, s[10:11]
	s_waitcnt vmcnt(0)

; DI unsigned xb_add(unsigned* p, unsigned v) { return __hip_atomic_fetch_add(p, v, __ATOMIC_RELAXED, __HIP_MEMORY_SCOPE_AGENT); }
; DI void xcd_barrier(const XcdBarrier& b) {
;     ...
;             __builtin_amdgcn_fence(__ATOMIC_ACQUIRE, "agent");
;             xb_add(&bar[XB_XGEN(b.x)], 1u);
;             asm volatile("s_waitcnt vmcnt(0)" ::: "memory");
.LBB0_918:
	s_or_b64 exec, exec, s[8:9]
	s_mov_b64 s[8:9], exec
	v_mbcnt_lo_u32_b32 v0, s8, 0
	v_mbcnt_hi_u32_b32 v0, s9, v0
	v_cmp_eq_u32_e32 vcc, 0, v0
	s_waitcnt vmcnt(0)
	buffer_inv sc1
	s_and_saveexec_b64 s[10:11], vcc
	s_cbranch_execz .LBB0_920
	s_bcnt1_i32_b64 s8, s[8:9]
	v_mov_b32_e32 v0, 0x2000
	v_mov_b32_e32 v1, s8
.LBB0_920:
	s_or_b64 exec, exec, s[10:11]
	s_waitcnt vmcnt(0)

; DI unsigned xb_add(unsigned* p, unsigned v) { return __hip_atomic_fetch_add(p, v, __ATOMIC_RELAXED, __HIP_MEMORY_SCOPE_AGENT); }
; DI void xcd_barrier(const XcdBarrier& b) {
;     ...
;             __builtin_amdgcn_fence(__ATOMIC_ACQUIRE, "agent");
;             xb_add(&bar[XB_XGEN(b.x)], 1u);
;             asm volatile("s_waitcnt vmcnt(0)" ::: "memory");
.LBB0_1061:
	s_or_b64 exec, exec, s[8:9]
	s_mov_b64 s[8:9], exec
	v_mbcnt_lo_u32_b32 v0, s8, 0
	v_mbcnt_hi_u32_b32 v0, s9, v0
	v_cmp_eq_u32_e32 vcc, 0, v0
	s_waitcnt vmcnt(0)
	buffer_inv sc1
	s_and_saveexec_b64 s[10:11], vcc
	s_cbranch_execz .LBB0_1063
	s_bcnt1_i32_b64 s8, s[8:9]
	v_mov_b32_e32 v0, 0x2000
	v_mov_b32_e32 v1, s8
.LBB0_1063:
	s_or_b64 exec, exec, s[10:11]
	s_waitcnt vmcnt(0)

; DI unsigned xb_ld(unsigned* p)              { return __hip_atomic_load(p, __ATOMIC_RELAXED, __HIP_MEMORY_SCOPE_AGENT); }
; DI unsigned xb_add(unsigned* p, unsigned v) { return __hip_atomic_fetch_add(p, v, __ATOMIC_RELAXED, __HIP_MEMORY_SCOPE_AGENT); }
; #define XB_SPIN(cond, bar) do { unsigned _sp = 0; while (cond) { __builtin_amdgcn_s_sleep(1); \
;     if ((++_sp & 255u) == 0u) { if (xb_ld(&(bar)[XB_TMO])) break; if (_sp > XB_SPIN_CAP) { atomicAdd(&(bar)[XB_TMO], 1u); break; } } } } while (0)
; DI void xcd_barrier(const XcdBarrier& b) {
;     ...
;             else XB_SPIN(xb_ld(&bar[XB_TOPGEN]) == tg, bar);
;             __builtin_amdgcn_fence(__ATOMIC_ACQUIRE, "agent");
;             xb_add(&bar[XB_XGEN(b.x)], 1u);
;             asm volatile("s_waitcnt vmcnt(0)" ::: "memory");
.Lsb4_lw:
	global_load_dword v161, v160, s[46:47] offset:1024 sc1
	s_waitcnt vmcnt(0)
	v_readfirstlane_b32 s79, v161
	s_cmp_lg_u32 s79, 3
	s_cbranch_scc1 .Lsb4_lead_go
	s_add_i32 s78, s78, 1
	s_cmp_lt_u32 s78, 0x800
	s_cbranch_scc0 .Lsb4_lead_go
	s_sleep 1
	s_branch .Lsb4_lw
.Lsb4_lead_go:
	buffer_inv sc1
	s_waitcnt vmcnt(0)
	s_branch .Lsb4_join

; DI unsigned xb_ld(unsigned* p)              { return __hip_atomic_load(p, __ATOMIC_RELAXED, __HIP_MEMORY_SCOPE_AGENT); }
; DI unsigned xb_add(unsigned* p, unsigned v) { return __hip_atomic_fetch_add(p, v, __ATOMIC_RELAXED, __HIP_MEMORY_SCOPE_AGENT); }
; #define XB_SPIN(cond, bar) do { unsigned _sp = 0; while (cond) { __builtin_amdgcn_s_sleep(1); \
;     if ((++_sp & 255u) == 0u) { if (xb_ld(&(bar)[XB_TMO])) break; if (_sp > XB_SPIN_CAP) { atomicAdd(&(bar)[XB_TMO], 1u); break; } } } } while (0)
; DI void xcd_barrier(const XcdBarrier& b) {
;     ...
;             else XB_SPIN(xb_ld(&bar[XB_TOPGEN]) == tg, bar);
;             __builtin_amdgcn_fence(__ATOMIC_ACQUIRE, "agent");
;             xb_add(&bar[XB_XGEN(b.x)], 1u);
;             asm volatile("s_waitcnt vmcnt(0)" ::: "memory");
.Lsb4b_lw:
	global_load_dword v161, v160, s[46:47] offset:1024 sc1
	s_waitcnt vmcnt(0)
	v_readfirstlane_b32 s79, v161
	s_cmp_lg_u32 s79, 3
	s_cbranch_scc1 .Lsb4b_lead_go
	s_add_i32 s78, s78, 1
	s_cmp_lt_u32 s78, 0x800
	s_cbranch_scc0 .Lsb4b_lead_go
	s_sleep 1
	s_branch .Lsb4b_lw
.Lsb4b_lead_go:
	buffer_inv sc1
	s_waitcnt vmcnt(0)
	s_branch .Lsb4b_join

; DI unsigned xb_ld(unsigned* p)              { return __hip_atomic_load(p, __ATOMIC_RELAXED, __HIP_MEMORY_SCOPE_AGENT); }
; DI unsigned xb_add(unsigned* p, unsigned v) { return __hip_atomic_fetch_add(p, v, __ATOMIC_RELAXED, __HIP_MEMORY_SCOPE_AGENT); }
; #define XB_SPIN(cond, bar) do { unsigned _sp = 0; while (cond) { __builtin_amdgcn_s_sleep(1); \
;     if ((++_sp & 255u) == 0u) { if (xb_ld(&(bar)[XB_TMO])) break; if (_sp > XB_SPIN_CAP) { atomicAdd(&(bar)[XB_TMO], 1u); break; } } } } while (0)
; DI void xcd_barrier(const XcdBarrier& b) {
;     ...
;             else XB_SPIN(xb_ld(&bar[XB_TOPGEN]) == tg, bar);
;             __builtin_amdgcn_fence(__ATOMIC_ACQUIRE, "agent");
;             xb_add(&bar[XB_XGEN(b.x)], 1u);
;             asm volatile("s_waitcnt vmcnt(0)" ::: "memory");
.Lsb_lw:
	global_load_dword v161, v160, s[46:47] offset:1024 sc1
	s_waitcnt vmcnt(0)
	v_readfirstlane_b32 s43, v161
	s_cmp_lg_u32 s43, 4
	s_cbranch_scc1 .Lsb_lead_go
	s_add_i32 s42, s42, 1
	s_cmp_lt_u32 s42, 0x800
	s_cbranch_scc0 .Lsb_lead_go
	s_sleep 1
	s_branch .Lsb_lw
.Lsb_lead_go:
	buffer_inv sc1
	s_waitcnt vmcnt(0)
	s_branch .Lsb_join
